# attention: K fragments for QK^T requested up front with counted LDS waits; P*V waits cover only the fragment the next MFMA consumes; K/V DMA bases in SGPRs
# speedup vs baseline: 1.0299x; 1.0044x over previous
.LBB0_843:
	s_or_b64 exec, exec, s[0:1]
	v_add_u32_e32 v181, s58, v153
	v_add_u32_e32 v182, v181, v160
	s_nop 2
	v_exp_f32_e32 v176, v80
	v_exp_f32_e32 v177, v81
	v_exp_f32_e32 v178, v82
	v_exp_f32_e32 v179, v83
	ds_read_b128 v[80:83], v182 offset:16384
	ds_read_b128 v[172:175], v182 offset:20480
	v_exp_f32_e32 v180, v84
	v_exp_f32_e32 v183, v85
	v_exp_f32_e32 v184, v86
	v_exp_f32_e32 v185, v87
	v_cvt_pk_bf16_f32 v84, v176, v177
	v_cvt_pk_bf16_f32 v85, v178, v179
	v_cvt_pk_bf16_f32 v86, v180, v183
	v_cvt_pk_bf16_f32 v87, v184, v185
	s_nop 1
	v_add_u32_e32 v189, v181, v161
	s_waitcnt lgkmcnt(1)
	v_mfma_f32_32x32x16_bf16 v[48:63], v[80:83], v[84:87], v[48:63]
	ds_read_b128 v[80:83], v182 offset:24576
	v_exp_f32_e32 v186, v88
	v_exp_f32_e32 v187, v90
	v_exp_f32_e32 v188, v91
	v_exp_f32_e32 v92, v92
	v_exp_f32_e32 v93, v93
	v_exp_f32_e32 v94, v94
	s_waitcnt lgkmcnt(1)
	v_mfma_f32_32x32x16_bf16 v[32:47], v[172:175], v[84:87], v[32:47]
	ds_read_b128 v[172:175], v182 offset:28672
	v_exp_f32_e32 v182, v89
	ds_read_b128 v[88:91], v189 offset:20480
	v_exp_f32_e32 v95, v95
	v_add_u32_e32 v191, v181, v162
	v_exp_f32_e32 v190, v69
	v_exp_f32_e32 v76, v76
	s_waitcnt lgkmcnt(2)
	v_mfma_f32_32x32x16_bf16 v[16:31], v[80:83], v[84:87], v[16:31]
	ds_read_b128 v[80:83], v189 offset:16384
	v_exp_f32_e32 v77, v77
	v_exp_f32_e32 v78, v78
	v_exp_f32_e32 v79, v79
	s_waitcnt lgkmcnt(2)
	v_mfma_f32_32x32x16_bf16 v[0:15], v[172:175], v[84:87], v[0:15]
	v_cvt_pk_bf16_f32 v84, v186, v182
	v_cvt_pk_bf16_f32 v85, v187, v188
	v_cvt_pk_bf16_f32 v86, v92, v93
	v_cvt_pk_bf16_f32 v87, v94, v95
	s_nop 1
	v_exp_f32_e32 v172, v64
	v_exp_f32_e32 v173, v65
	v_exp_f32_e32 v174, v66
	v_exp_f32_e32 v175, v67
	ds_read_b128 v[64:67], v191 offset:16384
	s_waitcnt lgkmcnt(1)
	v_mfma_f32_32x32x16_bf16 v[48:63], v[80:83], v[84:87], v[48:63]
	ds_read_b128 v[80:83], v189 offset:24576
	v_mfma_f32_32x32x16_bf16 v[32:47], v[88:91], v[84:87], v[32:47]
	ds_read_b128 v[88:91], v189 offset:28672
	v_exp_f32_e32 v189, v68
	s_waitcnt lgkmcnt(1)
	v_mfma_f32_32x32x16_bf16 v[16:31], v[80:83], v[84:87], v[16:31]
	ds_read_b128 v[80:83], v191 offset:20480
	s_waitcnt lgkmcnt(1)
	v_mfma_f32_32x32x16_bf16 v[0:15], v[88:91], v[84:87], v[0:15]
	v_exp_f32_e32 v84, v70
	v_exp_f32_e32 v85, v71
	v_cvt_pk_bf16_f32 v68, v172, v173
	v_cvt_pk_bf16_f32 v69, v174, v175
	v_cvt_pk_bf16_f32 v70, v189, v190
	v_cvt_pk_bf16_f32 v71, v84, v85
	s_nop 1
	v_add_u32_e32 v91, v181, v163
	v_exp_f32_e32 v87, v72
	v_exp_f32_e32 v88, v73
	v_exp_f32_e32 v89, v74
	v_mfma_f32_32x32x16_bf16 v[48:63], v[64:67], v[68:71], v[48:63]
	v_add_f32_e32 v64, 0, v176
	v_add_f32_e32 v64, v177, v64
	v_add_f32_e32 v64, v178, v64
	v_add_f32_e32 v64, v179, v64
	v_add_f32_e32 v64, v180, v64
	v_add_f32_e32 v86, v183, v64
	ds_read_b128 v[64:67], v191 offset:24576
	s_waitcnt lgkmcnt(1)
	v_mfma_f32_32x32x16_bf16 v[32:47], v[80:83], v[68:71], v[32:47]
	v_add_f32_e32 v80, v184, v86
	v_add_f32_e32 v80, v185, v80
	v_add_f32_e32 v80, v186, v80
	v_add_f32_e32 v80, v182, v80
	v_add_f32_e32 v86, v187, v80
	ds_read_b128 v[80:83], v191 offset:28672
	v_exp_f32_e32 v90, v75
	s_waitcnt lgkmcnt(1)
	v_mfma_f32_32x32x16_bf16 v[16:31], v[64:67], v[68:71], v[16:31]
	ds_read_b128 v[64:67], v91 offset:16384
	ds_read_b128 v[72:75], v91 offset:20480
	s_waitcnt lgkmcnt(2)
	v_mfma_f32_32x32x16_bf16 v[0:15], v[80:83], v[68:71], v[0:15]
	v_add_f32_e32 v68, v188, v86
	v_add_f32_e32 v68, v92, v68
	v_add_f32_e32 v80, v93, v68
	v_cvt_pk_bf16_f32 v68, v87, v88
	v_cvt_pk_bf16_f32 v69, v89, v90
	v_cvt_pk_bf16_f32 v70, v76, v77
	v_cvt_pk_bf16_f32 v71, v78, v79
	s_nop 1
	s_nop 0
	s_waitcnt lgkmcnt(1)
	v_mfma_f32_32x32x16_bf16 v[48:63], v[64:67], v[68:71], v[48:63]
	v_add_f32_e32 v64, v94, v80
	v_add_f32_e32 v64, v95, v64
	v_add_f32_e32 v64, v172, v64
	v_add_f32_e32 v64, v173, v64
	v_add_f32_e32 v64, v174, v64
	v_add_f32_e32 v80, v175, v64
	ds_read_b128 v[64:67], v91 offset:24576
	s_waitcnt lgkmcnt(1)
	v_mfma_f32_32x32x16_bf16 v[32:47], v[72:75], v[68:71], v[32:47]
	v_add_f32_e32 v72, v189, v80
	v_add_f32_e32 v72, v190, v72
	v_add_f32_e32 v72, v84, v72
	v_add_f32_e32 v72, v85, v72
	v_add_f32_e32 v72, v87, v72
	v_add_f32_e32 v80, v88, v72
	ds_read_b128 v[72:75], v91 offset:28672
	s_waitcnt lgkmcnt(1)
	v_mfma_f32_32x32x16_bf16 v[16:31], v[64:67], v[68:71], v[16:31]
	v_add_f32_e32 v64, v89, v80
	v_add_f32_e32 v64, v90, v64
	v_add_f32_e32 v64, v76, v64
	v_add_f32_e32 v64, v77, v64
	v_add_f32_e32 v64, v78, v64
	v_add_f32_e32 v64, v79, v64
	v_add_f32_e32 v131, v131, v64
	s_waitcnt lgkmcnt(0)
	v_mfma_f32_32x32x16_bf16 v[0:15], v[72:75], v[68:71], v[0:15]

.LBB0_847:
	s_or_b64 exec, exec, s[0:1]
	v_add_u32_e32 v133, 64, v172
	s_and_saveexec_b64 s[0:1], s[10:11]
	s_xor_b64 s[0:1], exec, s[0:1]
	v_add_u32_e32 v133, 64, v172
	s_andn2_saveexec_b64 s[48:49], s[0:1]
	s_cbranch_execz .LBB0_844
	s_lshl_b32 s0, s50, 15
	s_add_i32 s58, s0, 0
	v_add_u32_e32 v173, s58, v152
	v_add_u32_e32 v80, v173, v156
	v_add_u32_e32 v182, v173, v157
	v_add_u32_e32 v186, v173, v158
	ds_read_b128 v[174:177], v80
	ds_read_b128 v[178:181], v80 offset:8192
	ds_read_b128 v[208:211], v182
	ds_read_b128 v[182:185], v182 offset:8192
	ds_read_b128 v[212:215], v186
	ds_read_b128 v[186:189], v186 offset:8192
	v_add_u32_e32 v173, v173, v159
	v_cmp_gt_u32_e32 vcc, v133, v171
	s_waitcnt lgkmcnt(4)
	v_mfma_f32_32x32x16_bf16 v[80:95], v[174:177], v[96:99], v[232:247]
	v_mfma_f32_32x32x16_bf16 v[64:79], v[178:181], v[96:99], v[232:247]
	ds_read_b128 v[174:177], v173
	ds_read_b128 v[190:193], v173 offset:8192
	s_waitcnt lgkmcnt(4)
	v_mfma_f32_32x32x16_bf16 v[80:95], v[208:211], v[100:103], v[80:95]
	v_mfma_f32_32x32x16_bf16 v[64:79], v[182:185], v[100:103], v[64:79]
	s_waitcnt lgkmcnt(2)
	v_mfma_f32_32x32x16_bf16 v[80:95], v[212:215], v[104:107], v[80:95]
	v_mfma_f32_32x32x16_bf16 v[64:79], v[186:189], v[104:107], v[64:79]
	s_waitcnt lgkmcnt(0)
	v_mfma_f32_32x32x16_bf16 v[80:95], v[174:177], v[108:111], v[80:95]
	v_mfma_f32_32x32x16_bf16 v[64:79], v[190:193], v[108:111], v[64:79]
	s_and_saveexec_b64 s[50:51], vcc
	s_cbranch_execz .LBB0_852
	v_add_u32_e32 v172, v114, v172
	v_add_u32_e32 v173, 1, v172
	v_cmp_lt_u32_e32 vcc, v172, v171
	v_cmp_lt_u32_e64 s[0:1], v173, v171
	s_or_b64 vcc, s[0:1], vcc
	v_add_u32_e32 v173, 2, v172
	s_nop 2
	v_cndmask_b32_e32 v80, v169, v80, vcc
	v_cmp_lt_u32_e32 vcc, v173, v171
	v_add_u32_e32 v173, 3, v172
	v_cndmask_b32_e64 v81, v169, v81, s[0:1]
	v_cndmask_b32_e32 v82, v169, v82, vcc
	v_cmp_lt_u32_e32 vcc, v173, v171
	v_add_u32_e32 v173, 4, v172
	s_nop 0
	v_cndmask_b32_e32 v83, v169, v83, vcc
	v_cmp_lt_u32_e32 vcc, v173, v171
	v_add_u32_e32 v173, 5, v172
	s_nop 0
	v_cndmask_b32_e32 v84, v169, v84, vcc
	v_cmp_lt_u32_e32 vcc, v173, v171
	v_add_u32_e32 v173, 6, v172
	s_nop 0
	v_cndmask_b32_e32 v85, v169, v85, vcc
	v_cmp_lt_u32_e32 vcc, v173, v171
	v_add_u32_e32 v173, 7, v172
	s_nop 0
	v_cndmask_b32_e32 v86, v169, v86, vcc
	v_cmp_lt_u32_e32 vcc, v173, v171
	v_add_u32_e32 v173, 16, v172
	s_nop 0
	v_cndmask_b32_e32 v87, v169, v87, vcc
	v_cmp_lt_u32_e32 vcc, v173, v171
	v_add_u32_e32 v173, 17, v172
	s_nop 0
	v_cndmask_b32_e32 v88, v169, v88, vcc
	v_cmp_lt_u32_e32 vcc, v173, v171
	v_add_u32_e32 v173, 18, v172
	s_nop 0
	v_cndmask_b32_e32 v89, v169, v89, vcc
	v_cmp_lt_u32_e32 vcc, v173, v171
	v_add_u32_e32 v173, 19, v172
	s_nop 0
	v_cndmask_b32_e32 v90, v169, v90, vcc
	v_cmp_lt_u32_e32 vcc, v173, v171
	v_add_u32_e32 v173, 20, v172
	s_nop 0
	v_cndmask_b32_e32 v91, v169, v91, vcc
	v_cmp_lt_u32_e32 vcc, v173, v171
	v_add_u32_e32 v173, 21, v172
	s_nop 0
	v_cndmask_b32_e32 v92, v169, v92, vcc
	v_cmp_lt_u32_e32 vcc, v173, v171
	v_add_u32_e32 v173, 22, v172
	s_nop 0
	v_cndmask_b32_e32 v93, v169, v93, vcc
	v_cmp_lt_u32_e32 vcc, v173, v171
	v_add_u32_e32 v173, 23, v172
	s_nop 0
	v_cndmask_b32_e32 v94, v169, v94, vcc
	v_cmp_lt_u32_e32 vcc, v173, v171
	v_add_u32_e32 v173, 32, v172
	v_cmp_lt_u32_e64 s[0:1], v173, v171
	s_or_b64 vcc, s[0:1], vcc
	v_add_u32_e32 v173, 33, v172
	v_cndmask_b32_e32 v95, v169, v95, vcc
	v_cmp_lt_u32_e32 vcc, v173, v171
	v_add_u32_e32 v173, 34, v172
	v_cndmask_b32_e64 v64, v169, v64, s[0:1]
	v_cndmask_b32_e32 v65, v169, v65, vcc
	v_cmp_lt_u32_e32 vcc, v173, v171
	v_add_u32_e32 v173, 35, v172
	s_nop 0
	v_cndmask_b32_e32 v66, v169, v66, vcc
	v_cmp_lt_u32_e32 vcc, v173, v171
	v_add_u32_e32 v173, 36, v172
	s_nop 0
	v_cndmask_b32_e32 v67, v169, v67, vcc
	v_cmp_lt_u32_e32 vcc, v173, v171
	v_add_u32_e32 v173, 37, v172
	s_nop 0
	v_cndmask_b32_e32 v68, v169, v68, vcc
	v_cmp_lt_u32_e32 vcc, v173, v171
	v_add_u32_e32 v173, 38, v172
	s_nop 0
	v_cndmask_b32_e32 v69, v169, v69, vcc
	v_cmp_lt_u32_e32 vcc, v173, v171
	v_add_u32_e32 v173, 39, v172
	s_nop 0
	v_cndmask_b32_e32 v70, v169, v70, vcc
	v_cmp_lt_u32_e32 vcc, v173, v171
	v_add_u32_e32 v173, 48, v172
	s_nop 0
	v_cndmask_b32_e32 v71, v169, v71, vcc
	v_cmp_lt_u32_e32 vcc, v173, v171
	v_add_u32_e32 v173, 49, v172
	s_nop 0
	v_cndmask_b32_e32 v72, v169, v72, vcc
	v_cmp_lt_u32_e32 vcc, v173, v171
	v_add_u32_e32 v173, 50, v172
	s_nop 0
	v_cndmask_b32_e32 v73, v169, v73, vcc
	v_cmp_lt_u32_e32 vcc, v173, v171
	v_add_u32_e32 v173, 51, v172
	s_nop 0
	v_cndmask_b32_e32 v74, v169, v74, vcc
	v_cmp_lt_u32_e32 vcc, v173, v171
	v_add_u32_e32 v173, 52, v172
	s_nop 0
	v_cndmask_b32_e32 v75, v169, v75, vcc
	v_cmp_lt_u32_e32 vcc, v173, v171
	v_add_u32_e32 v173, 53, v172
	s_nop 0
	v_cndmask_b32_e32 v76, v169, v76, vcc
	v_cmp_lt_u32_e32 vcc, v173, v171
	v_add_u32_e32 v173, 54, v172
	v_add_u32_e32 v172, 55, v172
	v_cndmask_b32_e32 v77, v169, v77, vcc
	v_cmp_lt_u32_e32 vcc, v173, v171
	s_nop 1
	v_cndmask_b32_e32 v78, v169, v78, vcc
	v_cmp_lt_u32_e32 vcc, v172, v171
	s_nop 1
	v_cndmask_b32_e32 v79, v169, v79, vcc
